# MLA PV interleave, diff staging writes in QK gaps, dil2 and diff unit epilogue loads hoisted
# speedup vs baseline: 1.0278x; 1.0040x over previous
.LBB0_305:
	s_cmp_eq_u64 s[4:5], 0
	s_cbranch_scc1 .Ldil_nopf
	v_ashrrev_i32_e32 v239, 31, v126
	v_mov_b32_e32 v238, v126
	v_lshlrev_b64 v[234:235], 6, v[122:123]
	v_lshl_add_u64 v[234:235], s[62:63], 0, v[234:235]
	v_lshl_add_u64 v[234:235], v[238:239], 2, v[234:235]
	global_load_dword v240, v[234:235], off
	v_lshlrev_b64 v[230:231], 11, v[122:123]
	v_lshl_add_u64 v[230:231], s[36:37], 0, v[230:231]
	v_lshl_add_u64 v[230:231], v[124:125], 1, v[230:231]
	v_lshlrev_b32_e32 v232, 1, v129
	v_mov_b32_e32 v233, 0
	v_lshl_add_u64 v[230:231], v[230:231], 0, v[232:233]
	global_load_dwordx2 v[214:215], v[230:231], off
	global_load_dwordx2 v[216:217], v[230:231], off offset:16
	global_load_dwordx2 v[218:219], v[230:231], off offset:32
	global_load_dwordx2 v[220:221], v[230:231], off offset:48
	global_load_dwordx2 v[222:223], v[230:231], off offset:64
	global_load_dwordx2 v[224:225], v[230:231], off offset:80
	global_load_dwordx2 v[226:227], v[230:231], off offset:96
	global_load_dwordx2 v[228:229], v[230:231], off offset:112
.Ldil_nopf:
	v_mov_b32_e32 v0, v156
	s_nop 1
	v_permlane32_swap_b32_e32 v156, v0
	v_add_f32_e32 v0, v156, v0
	v_div_scale_f32 v36, s[0:1], v0, v0, 1.0
	v_log_f32_e32 v34, v0
	v_rcp_f32_e32 v37, v36
	v_ashrrev_i32_e32 v127, 31, v126
	s_waitcnt lgkmcnt(0)
	v_add_f32_e32 v35, v157, v34
	v_fma_f32 v34, -v36, v37, 1.0
	v_fmac_f32_e32 v37, v34, v37
	v_div_scale_f32 v34, vcc, 1.0, v0, 1.0
	v_mul_f32_e32 v38, v34, v37
	v_fma_f32 v39, -v36, v38, v34
	v_fmac_f32_e32 v38, v39, v37
	v_fma_f32 v34, -v36, v38, v34
	v_div_fmas_f32 v34, v34, v37, v38
	v_lshlrev_b64 v[36:37], 6, v[122:123]
	v_lshl_add_u64 v[36:37], s[62:63], 0, v[36:37]
	v_lshl_add_u64 v[38:39], v[126:127], 2, v[36:37]
	s_and_b64 vcc, exec, s[4:5]
	s_barrier
	s_cbranch_vccz .LBB0_307
	v_max_f32_e32 v36, v35, v35
	s_waitcnt vmcnt(0)
	v_mov_b32_e32 v34, v240
	v_max_f32_e32 v37, v34, v34
	v_max_f32_e32 v37, v37, v36
	v_sub_f32_e32 v34, v34, v37
	v_sub_f32_e32 v35, v35, v37
	v_exp_f32_e32 v34, v34
	v_exp_f32_e32 v35, v35
	s_nop 0
	v_add_f32_e32 v40, v34, v35
	v_div_scale_f32 v36, s[0:1], v40, v40, v34
	v_rcp_f32_e32 v41, v36
	v_mul_f32_e32 v0, v0, v40
	v_fma_f32 v42, -v36, v41, 1.0
	v_fmac_f32_e32 v41, v42, v41
	v_div_scale_f32 v42, vcc, v34, v40, v34
	v_mul_f32_e32 v43, v42, v41
	v_fma_f32 v44, -v36, v43, v42
	v_fmac_f32_e32 v43, v44, v41
	v_fma_f32 v36, -v36, v43, v42
	v_div_fmas_f32 v36, v36, v41, v43
	v_div_fixup_f32 v34, v36, v40, v34
	v_div_scale_f32 v36, s[0:1], v0, v0, v35
	v_rcp_f32_e32 v41, v36
	s_nop 0
	v_fma_f32 v42, -v36, v41, 1.0
	v_fmac_f32_e32 v41, v42, v41
	v_div_scale_f32 v42, vcc, v35, v0, v35
	v_mul_f32_e32 v43, v42, v41
	v_fma_f32 v44, -v36, v43, v42
	v_fmac_f32_e32 v43, v44, v41
	v_fma_f32 v36, -v36, v43, v42
	v_div_fmas_f32 v36, v36, v41, v43
	v_div_fixup_f32 v36, v36, v0, v35
	v_log_f32_e32 v0, v40
	s_nop 0
	v_add_f32_e32 v35, v37, v0
	v_cmp_gt_u32_e32 vcc, 32, v144
	s_and_saveexec_b64 s[0:1], vcc
	s_cbranch_execnz .LBB0_308
	s_branch .LBB0_309

.LBB0_309:
	s_or_b64 exec, exec, s[0:1]
	v_lshlrev_b64 v[38:39], 11, v[122:123]
	v_lshl_add_u64 v[38:39], s[36:37], 0, v[38:39]
	v_cndmask_b32_e64 v0, 0, 1, s[4:5]
	v_lshl_add_u64 v[38:39], v[124:125], 1, v[38:39]
	v_pk_mul_f32 v[2:3], v[2:3], v[36:37] op_sel_hi:[1,0]
	v_pk_mul_f32 v[4:5], v[4:5], v[36:37] op_sel_hi:[1,0]
	v_cmp_ne_u32_e64 s[2:3], 1, v0
	s_andn2_b64 vcc, exec, s[4:5]
	v_lshlrev_b32_e32 v0, 1, v129
	s_cbranch_vccnz .LBB0_311
	v_and_b32_e32 v43, 0xffff0000, v214
	v_lshlrev_b32_e32 v42, 16, v214
	v_pk_fma_f32 v[2:3], v[34:35], v[42:43], v[2:3] op_sel_hi:[0,1,1]
	v_and_b32_e32 v43, 0xffff0000, v215
	v_lshlrev_b32_e32 v42, 16, v215
	v_pk_fma_f32 v[4:5], v[34:35], v[42:43], v[4:5] op_sel_hi:[0,1,1]
.LBB0_311:
	v_mov_b32_e32 v37, v36
	v_cvt_pk_bf16_f32 v40, v2, v3
	v_cvt_pk_bf16_f32 v41, v4, v5
	v_lshl_add_u64 v[2:3], v[38:39], 0, v[0:1]
	v_pk_mul_f32 v[4:5], v[6:7], v[36:37]
	s_and_b64 vcc, exec, s[2:3]
	v_pk_mul_f32 v[6:7], v[8:9], v[36:37]
	global_store_dwordx2 v[2:3], v[40:41], off
	s_cbranch_vccnz .LBB0_313
	v_and_b32_e32 v39, 0xffff0000, v216
	v_lshlrev_b32_e32 v38, 16, v216
	v_pk_fma_f32 v[4:5], v[34:35], v[38:39], v[4:5] op_sel_hi:[0,1,1]
	v_and_b32_e32 v39, 0xffff0000, v217
	v_lshlrev_b32_e32 v38, 16, v217
	v_pk_fma_f32 v[6:7], v[34:35], v[38:39], v[6:7] op_sel_hi:[0,1,1]
.LBB0_313:
	v_cvt_pk_bf16_f32 v4, v4, v5
	v_cvt_pk_bf16_f32 v5, v6, v7
	global_store_dwordx2 v[2:3], v[4:5], off offset:16
	v_pk_mul_f32 v[4:5], v[10:11], v[36:37]
	s_and_b64 vcc, exec, s[2:3]
	v_pk_mul_f32 v[6:7], v[12:13], v[36:37]
	s_cbranch_vccnz .LBB0_315
	v_and_b32_e32 v11, 0xffff0000, v218
	v_lshlrev_b32_e32 v10, 16, v218
	v_pk_fma_f32 v[4:5], v[34:35], v[10:11], v[4:5] op_sel_hi:[0,1,1]
	v_and_b32_e32 v11, 0xffff0000, v219
	v_lshlrev_b32_e32 v10, 16, v219
	v_pk_fma_f32 v[6:7], v[34:35], v[10:11], v[6:7] op_sel_hi:[0,1,1]
.LBB0_315:
	v_cvt_pk_bf16_f32 v4, v4, v5
	v_cvt_pk_bf16_f32 v5, v6, v7
	global_store_dwordx2 v[2:3], v[4:5], off offset:32
	v_pk_mul_f32 v[4:5], v[14:15], v[36:37]
	s_and_b64 vcc, exec, s[2:3]
	v_pk_mul_f32 v[6:7], v[16:17], v[36:37]
	s_cbranch_vccnz .LBB0_317
	v_and_b32_e32 v11, 0xffff0000, v220
	v_lshlrev_b32_e32 v10, 16, v220
	v_pk_fma_f32 v[4:5], v[34:35], v[10:11], v[4:5] op_sel_hi:[0,1,1]
	v_and_b32_e32 v11, 0xffff0000, v221
	v_lshlrev_b32_e32 v10, 16, v221
	v_pk_fma_f32 v[6:7], v[34:35], v[10:11], v[6:7] op_sel_hi:[0,1,1]
.LBB0_317:
	v_cvt_pk_bf16_f32 v4, v4, v5
	v_cvt_pk_bf16_f32 v5, v6, v7
	global_store_dwordx2 v[2:3], v[4:5], off offset:48
	v_pk_mul_f32 v[4:5], v[18:19], v[36:37]
	s_and_b64 vcc, exec, s[2:3]
	v_pk_mul_f32 v[6:7], v[20:21], v[36:37]
	s_cbranch_vccnz .LBB0_319
	v_and_b32_e32 v11, 0xffff0000, v222
	v_lshlrev_b32_e32 v10, 16, v222
	v_pk_fma_f32 v[4:5], v[34:35], v[10:11], v[4:5] op_sel_hi:[0,1,1]
	v_and_b32_e32 v11, 0xffff0000, v223
	v_lshlrev_b32_e32 v10, 16, v223
	v_pk_fma_f32 v[6:7], v[34:35], v[10:11], v[6:7] op_sel_hi:[0,1,1]
.LBB0_319:
	v_cvt_pk_bf16_f32 v4, v4, v5
	v_cvt_pk_bf16_f32 v5, v6, v7
	global_store_dwordx2 v[2:3], v[4:5], off offset:64
	v_pk_mul_f32 v[4:5], v[22:23], v[36:37]
	s_and_b64 vcc, exec, s[2:3]
	v_pk_mul_f32 v[6:7], v[24:25], v[36:37]
	s_cbranch_vccnz .LBB0_321
	v_and_b32_e32 v11, 0xffff0000, v224
	v_lshlrev_b32_e32 v10, 16, v224
	v_pk_fma_f32 v[4:5], v[34:35], v[10:11], v[4:5] op_sel_hi:[0,1,1]
	v_and_b32_e32 v11, 0xffff0000, v225
	v_lshlrev_b32_e32 v10, 16, v225
	v_pk_fma_f32 v[6:7], v[34:35], v[10:11], v[6:7] op_sel_hi:[0,1,1]
.LBB0_321:
	v_cvt_pk_bf16_f32 v4, v4, v5
	v_cvt_pk_bf16_f32 v5, v6, v7
	global_store_dwordx2 v[2:3], v[4:5], off offset:80
	v_pk_mul_f32 v[4:5], v[26:27], v[36:37]
	s_and_b64 vcc, exec, s[2:3]
	v_pk_mul_f32 v[6:7], v[28:29], v[36:37]
	s_cbranch_vccnz .LBB0_323
	v_and_b32_e32 v11, 0xffff0000, v226
	v_lshlrev_b32_e32 v10, 16, v226
	v_pk_fma_f32 v[4:5], v[34:35], v[10:11], v[4:5] op_sel_hi:[0,1,1]
	v_and_b32_e32 v11, 0xffff0000, v227
	v_lshlrev_b32_e32 v10, 16, v227
	v_pk_fma_f32 v[6:7], v[34:35], v[10:11], v[6:7] op_sel_hi:[0,1,1]
.LBB0_323:
	v_cvt_pk_bf16_f32 v4, v4, v5
	v_cvt_pk_bf16_f32 v5, v6, v7
	global_store_dwordx2 v[2:3], v[4:5], off offset:96
	v_pk_mul_f32 v[4:5], v[30:31], v[36:37]
	s_and_b64 vcc, exec, s[2:3]
	v_pk_mul_f32 v[6:7], v[32:33], v[36:37]
	s_cbranch_vccnz .LBB0_284
	v_and_b32_e32 v11, 0xffff0000, v228
	v_lshlrev_b32_e32 v10, 16, v228
	v_pk_fma_f32 v[4:5], v[34:35], v[10:11], v[4:5] op_sel_hi:[0,1,1]
	v_and_b32_e32 v11, 0xffff0000, v229
	v_lshlrev_b32_e32 v10, 16, v229
	v_pk_fma_f32 v[6:7], v[34:35], v[10:11], v[6:7] op_sel_hi:[0,1,1]
	s_branch .LBB0_284

.LBB0_666:
	s_add_u32 s0, s0, 0x40000
	s_addc_u32 s1, s1, 0
	s_add_i32 s10, s10, 1
	s_cmp_lg_u32 s0, 0x1000000
	v_lshl_add_u64 v[128:129], v[128:129], 0, s[40:41]
	s_cbranch_scc0 .LBB0_655

.LBB0_673:
	v_exp_f32_e32 v66, v66
	v_exp_f32_e32 v67, v67
	v_exp_f32_e32 v68, v68
	v_exp_f32_e32 v69, v69
	v_exp_f32_e32 v70, v70
	v_exp_f32_e32 v71, v71
	v_exp_f32_e32 v72, v72
	v_exp_f32_e32 v73, v73
	v_cvt_pk_bf16_f32 v146, v66, v67
	v_cvt_pk_bf16_f32 v147, v68, v69
	v_cvt_pk_bf16_f32 v148, v70, v71
	v_cvt_pk_bf16_f32 v149, v72, v73
	ds_read_b64_tr_b16 v[182:183], v0 offset:16384
	ds_read_b64_tr_b16 v[184:185], v0 offset:17920
	ds_read_b64_tr_b16 v[188:189], v0 offset:17984
	ds_read_b64_tr_b16 v[186:187], v0 offset:16448
	s_setprio 1
	s_waitcnt lgkmcnt(6)
	v_mfma_f32_32x32x16_bf16 v[2:17], v[122:125], v[146:149], v[2:17]
	v_exp_f32_e32 v74, v74
	v_exp_f32_e32 v75, v75
	v_add_f32_e32 v218, v68, v66
	v_add_f32_e32 v219, v67, v69
	s_waitcnt lgkmcnt(4)
	v_mfma_f32_32x32x16_bf16 v[18:33], v[118:121], v[146:149], v[18:33]
	v_exp_f32_e32 v76, v76
	v_exp_f32_e32 v77, v77
	v_cvt_pk_bf16_f32 v150, v74, v75
	v_add_f32_e32 v218, v218, v70
	v_exp_f32_e32 v78, v78
	v_exp_f32_e32 v79, v79
	v_exp_f32_e32 v80, v80
	v_exp_f32_e32 v81, v81
	v_cvt_pk_bf16_f32 v151, v76, v77
	v_cvt_pk_bf16_f32 v152, v78, v79
	v_cvt_pk_bf16_f32 v153, v80, v81
	s_setprio 0
	ds_read_b64_tr_b16 v[118:119], v0 offset:19456
	ds_read_b64_tr_b16 v[120:121], v0 offset:20992
	ds_read_b64_tr_b16 v[124:125], v0 offset:21056
	ds_read_b64_tr_b16 v[122:123], v0 offset:19520
	s_setprio 1
	s_waitcnt lgkmcnt(6)
	v_mfma_f32_32x32x16_bf16 v[2:17], v[182:185], v[150:153], v[2:17]
	v_exp_f32_e32 v144, v50
	v_exp_f32_e32 v145, v51
	v_add_f32_e32 v219, v71, v219
	v_add_f32_e32 v218, v72, v218
	s_waitcnt lgkmcnt(4)
	v_mfma_f32_32x32x16_bf16 v[18:33], v[186:189], v[150:153], v[18:33]
	v_exp_f32_e32 v52, v52
	v_exp_f32_e32 v53, v53
	v_cvt_pk_bf16_f32 v154, v144, v145
	v_add_f32_e32 v219, v73, v219
	v_exp_f32_e32 v54, v54
	v_exp_f32_e32 v55, v55
	v_exp_f32_e32 v56, v56
	v_exp_f32_e32 v57, v57
	v_cvt_pk_bf16_f32 v155, v52, v53
	v_cvt_pk_bf16_f32 v156, v54, v55
	v_cvt_pk_bf16_f32 v157, v56, v57
	s_setprio 0
	ds_read_b64_tr_b16 v[146:147], v0 offset:22528
	ds_read_b64_tr_b16 v[148:149], v0 offset:24064
	ds_read_b64_tr_b16 v[152:153], v0 offset:24128
	ds_read_b64_tr_b16 v[150:151], v0 offset:22592
	s_setprio 1
	s_waitcnt lgkmcnt(6)
	v_mfma_f32_32x32x16_bf16 v[2:17], v[118:121], v[154:157], v[2:17]
	v_exp_f32_e32 v58, v58
	v_exp_f32_e32 v59, v59
	v_add_f32_e32 v218, v74, v218
	v_add_f32_e32 v219, v75, v219
	s_waitcnt lgkmcnt(4)
	v_mfma_f32_32x32x16_bf16 v[18:33], v[122:125], v[154:157], v[18:33]
	v_exp_f32_e32 v60, v60
	v_exp_f32_e32 v61, v61
	v_cvt_pk_bf16_f32 v214, v58, v59
	v_add_f32_e32 v218, v76, v218
	v_exp_f32_e32 v62, v62
	v_exp_f32_e32 v63, v63
	v_exp_f32_e32 v64, v64
	v_exp_f32_e32 v65, v65
	v_cvt_pk_bf16_f32 v215, v60, v61
	v_cvt_pk_bf16_f32 v216, v62, v63
	v_cvt_pk_bf16_f32 v217, v64, v65
	s_nop 1
	s_waitcnt lgkmcnt(2)
	v_mfma_f32_32x32x16_bf16 v[2:17], v[146:149], v[214:217], v[2:17]
	v_add_f32_e32 v219, v77, v219
	v_add_f32_e32 v218, v78, v218
	v_add_f32_e32 v219, v79, v219
	v_add_f32_e32 v218, v80, v218
	v_add_f32_e32 v219, v81, v219
	v_add_f32_e32 v218, v144, v218
	s_waitcnt lgkmcnt(0)
	v_mfma_f32_32x32x16_bf16 v[18:33], v[150:153], v[214:217], v[18:33]
	s_setprio 0
	v_add_f32_e32 v219, v145, v219
	v_add_f32_e32 v218, v52, v218
	v_add_f32_e32 v219, v53, v219
	v_add_f32_e32 v218, v54, v218
	v_add_f32_e32 v219, v55, v219
	v_add_f32_e32 v218, v56, v218
	v_add_f32_e32 v219, v57, v219
	v_add_f32_e32 v218, v58, v218
	v_add_f32_e32 v219, v59, v219
	v_add_f32_e32 v218, v60, v218
	v_add_f32_e32 v219, v61, v219
	v_add_f32_e32 v218, v62, v218
	v_add_f32_e32 v219, v63, v219
	v_add_f32_e32 v218, v64, v218
	v_add_f32_e32 v219, v65, v219
	v_add_f32_e32 v218, v218, v219
	v_add_f32_e32 v142, v142, v218
	s_cmp_eq_u32 s0, 0xfc0000
	s_cbranch_scc1 .LBB0_666
	s_xor_b32 s4, s11, 1
	s_mulk_i32 s4, 0x6400
	s_add_i32 s6, s4, 0
	v_add3_u32 v0, s6, v134, v133
	s_waitcnt vmcnt(1)
	ds_write_b128 v0, v[110:113]
	s_and_saveexec_b64 s[4:5], s[2:3]
	v_add3_u32 v0, s6, v135, v136
	ds_write_b128 v0, v[106:109] offset:128
	s_or_b64 exec, exec, s[4:5]
	v_add3_u32 v0, s6, v137, v133
	s_cmp_gt_u32 s10, 61
	s_waitcnt vmcnt(0)
	ds_write_b128 v0, v[114:117] offset:13312
	s_cbranch_scc1 .LBB0_666
	v_lshl_add_u64 v[50:51], v[130:131], 0, s[0:1]
	v_add_co_u32_e32 v110, vcc, 0x15080000, v50
	s_nop 1
	v_addc_co_u32_e32 v111, vcc, 0, v51, vcc
	global_load_dwordx4 v[110:113], v[110:111], off
	s_and_saveexec_b64 s[4:5], s[2:3]
	s_cbranch_execz .LBB0_665
	global_load_dwordx4 v[106:109], v[128:129], off
	s_branch .LBB0_665

.LBB0_795:
	global_load_dwordx4 v[12:15], v182, s[0:1]
	global_load_dwordx4 v[16:19], v182, s[0:1] offset:32
	global_load_dwordx4 v[20:23], v182, s[0:1] offset:64
	global_load_dwordx4 v[24:27], v182, s[0:1] offset:96
	global_load_dwordx4 v[28:31], v182, s[0:1] offset:128
	global_load_dwordx4 v[32:35], v182, s[0:1] offset:160
	global_load_dwordx4 v[36:39], v182, s[0:1] offset:192
	global_load_dwordx4 v[40:43], v182, s[0:1] offset:224
	global_load_dwordx4 v[44:47], v182, s[0:1] offset:256
	global_load_dwordx4 v[48:51], v182, s[0:1] offset:288
	global_load_dwordx4 v[52:55], v182, s[0:1] offset:320
	global_load_dwordx4 v[56:59], v182, s[0:1] offset:352
	global_load_dwordx4 v[60:63], v182, s[0:1] offset:384
	global_load_dwordx4 v[214:217], v182, s[0:1] offset:416
	global_load_dwordx4 v[218:221], v182, s[0:1] offset:448
	global_load_dwordx4 v[222:225], v182, s[0:1] offset:480
	v_mul_f32_e32 v0, v129, v129
	v_fmac_f32_e32 v0, v128, v128
	v_fmac_f32_e32 v0, v126, v126
	v_fmac_f32_e32 v0, v127, v127
	v_fmac_f32_e32 v0, v124, v124
	v_fmac_f32_e32 v0, v125, v125
	v_fmac_f32_e32 v0, v122, v122
	v_fmac_f32_e32 v0, v123, v123
	v_fmac_f32_e32 v0, v120, v120
	v_fmac_f32_e32 v0, v121, v121
	v_fmac_f32_e32 v0, v118, v118
	v_fmac_f32_e32 v0, v119, v119
	v_fmac_f32_e32 v0, v114, v114
	v_fmac_f32_e32 v0, v115, v115
	v_fmac_f32_e32 v0, v112, v112
	v_fmac_f32_e32 v0, v113, v113
	v_fmac_f32_e32 v0, v116, v116
	v_fmac_f32_e32 v0, v117, v117
	v_fmac_f32_e32 v0, v110, v110
	v_fmac_f32_e32 v0, v111, v111
	v_fmac_f32_e32 v0, v108, v108
	v_fmac_f32_e32 v0, v109, v109
	v_fmac_f32_e32 v0, v106, v106
	v_fmac_f32_e32 v0, v107, v107
	v_fmac_f32_e32 v0, v104, v104
	v_fmac_f32_e32 v0, v105, v105
	v_fmac_f32_e32 v0, v102, v102
	v_fmac_f32_e32 v0, v103, v103
	v_fmac_f32_e32 v0, v98, v98
	v_fmac_f32_e32 v0, v99, v99
	v_fmac_f32_e32 v0, v96, v96
	v_fmac_f32_e32 v0, v97, v97
	v_fmac_f32_e32 v0, v100, v100
	v_fmac_f32_e32 v0, v101, v101
	v_fmac_f32_e32 v0, v94, v94
	v_fmac_f32_e32 v0, v95, v95
	v_fmac_f32_e32 v0, v92, v92
	v_fmac_f32_e32 v0, v93, v93
	v_fmac_f32_e32 v0, v90, v90
	v_fmac_f32_e32 v0, v91, v91
	v_fmac_f32_e32 v0, v88, v88
	v_fmac_f32_e32 v0, v89, v89
	v_fmac_f32_e32 v0, v86, v86
	v_fmac_f32_e32 v0, v87, v87
	v_fmac_f32_e32 v0, v82, v82
	v_fmac_f32_e32 v0, v83, v83
	v_fmac_f32_e32 v0, v80, v80
	v_fmac_f32_e32 v0, v81, v81
	v_fmac_f32_e32 v0, v84, v84
	v_fmac_f32_e32 v0, v85, v85
	v_fmac_f32_e32 v0, v78, v78
	v_fmac_f32_e32 v0, v79, v79
	v_fmac_f32_e32 v0, v76, v76
	v_fmac_f32_e32 v0, v77, v77
	v_fmac_f32_e32 v0, v74, v74
	v_fmac_f32_e32 v0, v75, v75
	v_fmac_f32_e32 v0, v72, v72
	v_fmac_f32_e32 v0, v73, v73
	v_fmac_f32_e32 v0, v70, v70
	v_fmac_f32_e32 v0, v71, v71
	v_fmac_f32_e32 v0, v66, v66
	v_fmac_f32_e32 v0, v67, v67
	v_pk_mul_f32 v[2:3], v[68:69], v[68:69]
	s_lshl_b32 s90, s23, 1
	v_add_f32_e32 v0, v2, v0
	v_add_f32_e32 v0, v3, v0
	v_mov_b32_e32 v2, v0
	s_nop 1
	v_permlane32_swap_b32_e32 v0, v2
	v_add_f32_e32 v0, v0, v2
	v_lshlrev_b64 v[2:3], 11, v[184:185]
	v_lshl_add_u64 v[2:3], s[36:37], 0, v[2:3]
	v_lshl_add_u64 v[8:9], v[2:3], 0, s[90:91]
	v_fmamk_f32 v0, v0, 0x3c000000, v195
	v_rsq_f32_e32 v0, v0
	s_add_i32 s14, s14, 1
	s_add_i32 s22, s22, 8
	s_cmp_eq_u32 s14, s33
	v_mul_f32_e32 v6, v202, v0
	v_pk_mul_f32 v[10:11], v[128:129], v[6:7] op_sel_hi:[1,0]
	v_lshlrev_b32_e32 v0, 3, v203
	s_cselect_b64 s[2:3], -1, 0
	s_waitcnt vmcnt(0)
	v_pk_mul_f32 v[2:3], v[12:13], v[10:11]
	s_nop 0
	v_cvt_pk_bf16_f32 v10, v2, v3
	v_pk_mul_f32 v[2:3], v[126:127], v[6:7] op_sel_hi:[1,0]
	s_nop 0
	v_pk_mul_f32 v[2:3], v[14:15], v[2:3]
	v_pk_mul_f32 v[4:5], v[124:125], v[6:7] op_sel_hi:[1,0]
	v_cvt_pk_bf16_f32 v11, v2, v3
	v_lshl_add_u64 v[2:3], v[8:9], 0, v[0:1]
	global_store_dwordx2 v[2:3], v[10:11], off
	v_pk_mul_f32 v[4:5], v[16:17], v[4:5]
	v_pk_mul_f32 v[8:9], v[122:123], v[6:7] op_sel_hi:[1,0]
	v_cvt_pk_bf16_f32 v4, v4, v5
	v_pk_mul_f32 v[8:9], v[18:19], v[8:9]
	s_nop 0
	v_cvt_pk_bf16_f32 v5, v8, v9
	global_store_dwordx2 v[2:3], v[4:5], off offset:16
	v_pk_mul_f32 v[4:5], v[120:121], v[6:7] op_sel_hi:[1,0]
	v_pk_mul_f32 v[4:5], v[20:21], v[4:5]
	v_pk_mul_f32 v[8:9], v[118:119], v[6:7] op_sel_hi:[1,0]
	v_cvt_pk_bf16_f32 v4, v4, v5
	v_pk_mul_f32 v[8:9], v[22:23], v[8:9]
	s_nop 0
	v_cvt_pk_bf16_f32 v5, v8, v9
	global_store_dwordx2 v[2:3], v[4:5], off offset:32
	v_pk_mul_f32 v[4:5], v[114:115], v[6:7] op_sel_hi:[1,0]
	v_pk_mul_f32 v[4:5], v[24:25], v[4:5]
	v_pk_mul_f32 v[8:9], v[112:113], v[6:7] op_sel_hi:[1,0]
	v_cvt_pk_bf16_f32 v4, v4, v5
	v_pk_mul_f32 v[8:9], v[26:27], v[8:9]
	s_nop 0
	v_cvt_pk_bf16_f32 v5, v8, v9
	global_store_dwordx2 v[2:3], v[4:5], off offset:48
	v_pk_mul_f32 v[4:5], v[116:117], v[6:7] op_sel_hi:[1,0]
	v_pk_mul_f32 v[4:5], v[4:5], v[28:29]
	v_pk_mul_f32 v[8:9], v[110:111], v[6:7] op_sel_hi:[1,0]
	v_cvt_pk_bf16_f32 v4, v4, v5
	v_pk_mul_f32 v[8:9], v[8:9], v[30:31]
	s_nop 0
	v_cvt_pk_bf16_f32 v5, v8, v9
	global_store_dwordx2 v[2:3], v[4:5], off offset:64
	v_pk_mul_f32 v[4:5], v[108:109], v[6:7] op_sel_hi:[1,0]
	v_pk_mul_f32 v[4:5], v[4:5], v[32:33]
	v_pk_mul_f32 v[8:9], v[106:107], v[6:7] op_sel_hi:[1,0]
	v_cvt_pk_bf16_f32 v4, v4, v5
	v_pk_mul_f32 v[8:9], v[8:9], v[34:35]
	s_nop 0
	v_cvt_pk_bf16_f32 v5, v8, v9
	global_store_dwordx2 v[2:3], v[4:5], off offset:80
	v_pk_mul_f32 v[4:5], v[104:105], v[6:7] op_sel_hi:[1,0]
	v_pk_mul_f32 v[4:5], v[4:5], v[36:37]
	v_pk_mul_f32 v[8:9], v[102:103], v[6:7] op_sel_hi:[1,0]
	v_cvt_pk_bf16_f32 v4, v4, v5
	v_pk_mul_f32 v[8:9], v[8:9], v[38:39]
	s_nop 0
	v_cvt_pk_bf16_f32 v5, v8, v9
	global_store_dwordx2 v[2:3], v[4:5], off offset:96
	v_pk_mul_f32 v[4:5], v[98:99], v[6:7] op_sel_hi:[1,0]
	v_pk_mul_f32 v[4:5], v[4:5], v[40:41]
	v_pk_mul_f32 v[8:9], v[96:97], v[6:7] op_sel_hi:[1,0]
	v_cvt_pk_bf16_f32 v4, v4, v5
	v_pk_mul_f32 v[8:9], v[8:9], v[42:43]
	s_nop 0
	v_cvt_pk_bf16_f32 v5, v8, v9
	global_store_dwordx2 v[2:3], v[4:5], off offset:112
	v_pk_mul_f32 v[4:5], v[100:101], v[6:7] op_sel_hi:[1,0]
	v_pk_mul_f32 v[4:5], v[4:5], v[44:45]
	v_pk_mul_f32 v[8:9], v[94:95], v[6:7] op_sel_hi:[1,0]
	v_cvt_pk_bf16_f32 v4, v4, v5
	v_pk_mul_f32 v[8:9], v[8:9], v[46:47]
	s_nop 0
	v_cvt_pk_bf16_f32 v5, v8, v9
	global_store_dwordx2 v[2:3], v[4:5], off offset:128
	v_pk_mul_f32 v[4:5], v[92:93], v[6:7] op_sel_hi:[1,0]
	v_pk_mul_f32 v[4:5], v[4:5], v[48:49]
	v_pk_mul_f32 v[8:9], v[90:91], v[6:7] op_sel_hi:[1,0]
	v_cvt_pk_bf16_f32 v4, v4, v5
	v_pk_mul_f32 v[8:9], v[8:9], v[50:51]
	s_nop 0
	v_cvt_pk_bf16_f32 v5, v8, v9
	global_store_dwordx2 v[2:3], v[4:5], off offset:144
	v_pk_mul_f32 v[4:5], v[88:89], v[6:7] op_sel_hi:[1,0]
	v_pk_mul_f32 v[4:5], v[4:5], v[52:53]
	v_pk_mul_f32 v[8:9], v[86:87], v[6:7] op_sel_hi:[1,0]
	v_cvt_pk_bf16_f32 v4, v4, v5
	v_pk_mul_f32 v[8:9], v[8:9], v[54:55]
	s_nop 0
	v_cvt_pk_bf16_f32 v5, v8, v9
	global_store_dwordx2 v[2:3], v[4:5], off offset:160
	v_pk_mul_f32 v[4:5], v[82:83], v[6:7] op_sel_hi:[1,0]
	v_pk_mul_f32 v[4:5], v[4:5], v[56:57]
	v_pk_mul_f32 v[8:9], v[80:81], v[6:7] op_sel_hi:[1,0]
	v_cvt_pk_bf16_f32 v4, v4, v5
	v_pk_mul_f32 v[8:9], v[8:9], v[58:59]
	s_nop 0
	v_cvt_pk_bf16_f32 v5, v8, v9
	global_store_dwordx2 v[2:3], v[4:5], off offset:176
	v_pk_mul_f32 v[4:5], v[84:85], v[6:7] op_sel_hi:[1,0]
	v_pk_mul_f32 v[4:5], v[4:5], v[60:61]
	v_pk_mul_f32 v[8:9], v[78:79], v[6:7] op_sel_hi:[1,0]
	v_cvt_pk_bf16_f32 v4, v4, v5
	v_pk_mul_f32 v[8:9], v[8:9], v[62:63]
	s_nop 0
	v_cvt_pk_bf16_f32 v5, v8, v9
	global_store_dwordx2 v[2:3], v[4:5], off offset:192
	v_pk_mul_f32 v[4:5], v[76:77], v[6:7] op_sel_hi:[1,0]
	v_pk_mul_f32 v[4:5], v[4:5], v[214:215]
	v_pk_mul_f32 v[8:9], v[74:75], v[6:7] op_sel_hi:[1,0]
	v_cvt_pk_bf16_f32 v4, v4, v5
	v_pk_mul_f32 v[8:9], v[8:9], v[216:217]
	s_nop 0
	v_cvt_pk_bf16_f32 v5, v8, v9
	global_store_dwordx2 v[2:3], v[4:5], off offset:208
	v_pk_mul_f32 v[4:5], v[72:73], v[6:7] op_sel_hi:[1,0]
	v_pk_mul_f32 v[4:5], v[4:5], v[218:219]
	v_pk_mul_f32 v[8:9], v[70:71], v[6:7] op_sel_hi:[1,0]
	v_cvt_pk_bf16_f32 v4, v4, v5
	v_pk_mul_f32 v[8:9], v[8:9], v[220:221]
	s_nop 0
	v_cvt_pk_bf16_f32 v5, v8, v9
	global_store_dwordx2 v[2:3], v[4:5], off offset:224
	v_pk_mul_f32 v[4:5], v[66:67], v[6:7] op_sel_hi:[1,0]
	v_pk_mul_f32 v[6:7], v[68:69], v[6:7] op_sel_hi:[1,0]
	v_pk_mul_f32 v[4:5], v[4:5], v[222:223]
	v_pk_mul_f32 v[6:7], v[6:7], v[224:225]
	v_cvt_pk_bf16_f32 v4, v4, v5
	v_cvt_pk_bf16_f32 v5, v6, v7
	global_store_dwordx2 v[2:3], v[4:5], off offset:240

.LBB0_802:
	s_and_b32 s30, s29, 1
	s_mul_i32 s12, s30, 0x7400
	s_add_i32 s12, s12, 0
	v_add3_u32 v86, s12, v208, v209
	s_waitcnt lgkmcnt(0)
	s_barrier
	ds_read_b128 v[82:85], v86
	ds_read_b128 v[142:145], v86 offset:32
	ds_read_b128 v[146:149], v86 offset:4608
	ds_read_b128 v[150:153], v86 offset:4640
	ds_read_b128 v[154:157], v86 offset:64
	ds_read_b128 v[214:217], v86 offset:96
	ds_read_b128 v[218:221], v86 offset:4672
	ds_read_b128 v[222:225], v86 offset:4704
	s_cmp_eq_u32 s10, 0
	s_cselect_b64 s[16:17], -1, 0
	s_cmp_lg_u32 s10, 0
	v_add_u32_e32 v86, s12, v210
	s_cselect_b64 s[18:19], -1, 0
	v_add_u32_e32 v213, v86, v211
	s_cmp_gt_u32 s29, 61
	s_cbranch_scc1 .Ld_plainqk
	s_xor_b32 s12, s30, 1
	s_mulk_i32 s12, 0x7400
	v_add3_u32 v246, s12, v206, v183
	v_add3_u32 v247, s12, v205, v207
	s_setprio 1
	s_waitcnt lgkmcnt(7)
	v_mfma_f32_32x32x16_bf16 v[98:113], v[82:85], v[114:117], v[66:81]
	s_waitcnt vmcnt(2)
	ds_write_b128 v246, v[130:133]
	s_waitcnt lgkmcnt(7)
	v_mfma_f32_32x32x16_bf16 v[98:113], v[142:145], v[118:121], v[98:113]
	s_waitcnt vmcnt(1)
	ds_write_b128 v247, v[134:137] offset:9216
	s_waitcnt lgkmcnt(7)
	v_mfma_f32_32x32x16_bf16 v[82:97], v[146:149], v[114:117], v[66:81]
	s_waitcnt vmcnt(0)
	ds_write_b128 v247, v[138:141] offset:19456
	s_waitcnt lgkmcnt(7)
	v_mfma_f32_32x32x16_bf16 v[82:97], v[150:153], v[118:121], v[82:97]
	v_lshl_add_u64 v[130:131], v[188:189], 0, s[10:11]
	global_load_dwordx4 v[130:133], v[130:131], off
	s_waitcnt lgkmcnt(6)
	v_mfma_f32_32x32x16_bf16 v[98:113], v[154:157], v[122:125], v[98:113]
	v_lshl_add_u64 v[134:135], v[190:191], 0, s[10:11]
	global_load_dwordx4 v[134:137], v[134:135], off
	s_waitcnt lgkmcnt(4)
	v_mfma_f32_32x32x16_bf16 v[82:97], v[218:221], v[122:125], v[82:97]
	v_lshl_add_u64 v[138:139], v[192:193], 0, s[10:11]
	global_load_dwordx4 v[138:141], v[138:139], off
	v_mfma_f32_32x32x16_bf16 v[98:113], v[214:217], v[126:129], v[98:113]
	s_waitcnt lgkmcnt(3)
	v_mfma_f32_32x32x16_bf16 v[82:97], v[222:225], v[126:129], v[82:97]
	s_setprio 0
	s_branch .Ld_qkjoin
.Ld_plainqk:
	s_setprio 1
	s_waitcnt lgkmcnt(7)
	v_mfma_f32_32x32x16_bf16 v[98:113], v[82:85], v[114:117], v[66:81]
	s_waitcnt lgkmcnt(6)
	v_mfma_f32_32x32x16_bf16 v[98:113], v[142:145], v[118:121], v[98:113]
	s_waitcnt lgkmcnt(5)
	v_mfma_f32_32x32x16_bf16 v[82:97], v[146:149], v[114:117], v[66:81]
	s_waitcnt lgkmcnt(4)
	v_mfma_f32_32x32x16_bf16 v[82:97], v[150:153], v[118:121], v[82:97]
	s_waitcnt lgkmcnt(3)
	v_mfma_f32_32x32x16_bf16 v[98:113], v[154:157], v[122:125], v[98:113]
	s_waitcnt lgkmcnt(1)
	v_mfma_f32_32x32x16_bf16 v[82:97], v[218:221], v[122:125], v[82:97]
	v_mfma_f32_32x32x16_bf16 v[98:113], v[214:217], v[126:129], v[98:113]
	s_waitcnt lgkmcnt(0)
	v_mfma_f32_32x32x16_bf16 v[82:97], v[222:225], v[126:129], v[82:97]
	s_setprio 0
.Ld_qkjoin:
	ds_read_b64_tr_b16 v[154:155], v213 offset:9216
	ds_read_b64_tr_b16 v[150:151], v213 offset:9280
	ds_read_b64_tr_b16 v[146:147], v213 offset:9344
	ds_read_b64_tr_b16 v[142:143], v213 offset:9408
	ds_read_b64_tr_b16 v[156:157], v213 offset:11776
	ds_read_b64_tr_b16 v[152:153], v213 offset:11840
	ds_read_b64_tr_b16 v[148:149], v213 offset:11904
	ds_read_b64_tr_b16 v[144:145], v213 offset:11968
	s_nop 0
	v_max_f32_e32 v214, v100, v100
	s_nop 0
	v_max_f32_e32 v215, v83, v83
	v_max_f32_e32 v214, v215, v214
	v_max3_f32 v200, v98, v82, v99
	v_max3_f32 v214, v214, v84, v102
	v_max3_f32 v200, v200, v101, v85
	v_max3_f32 v214, v214, v86, v104
	v_max3_f32 v200, v200, v103, v87
	v_max3_f32 v214, v214, v88, v106
	v_max3_f32 v200, v200, v105, v89
	v_max3_f32 v214, v214, v90, v108
	v_max3_f32 v200, v200, v107, v91
	v_max3_f32 v214, v214, v92, v110
	v_max3_f32 v200, v200, v109, v93
	v_max3_f32 v214, v214, v94, v112
	v_max3_f32 v200, v200, v111, v95
	v_max3_f32 v214, v214, v96, v97
	v_max3_f32 v200, v200, v113, v214
	v_mov_b32_e32 v214, v200
	s_nop 1
	v_permlane32_swap_b32_e32 v200, v214
	v_max_f32_e32 v214, v214, v214
	v_max_f32_e32 v200, v200, v200
	v_max_f32_e32 v214, v200, v214
	s_and_b64 vcc, exec, s[16:17]
	s_mov_b64 s[20:21], s[16:17]
	s_cbranch_vccnz .LBB0_804
	v_cmp_lt_f32_e32 vcc, s61, v214
	s_cmp_lg_u64 vcc, 0
	s_cselect_b64 s[20:21], -1, 0

.LBB0_808:
	v_exp_f32_e32 v98, v98
	v_exp_f32_e32 v99, v99
	v_exp_f32_e32 v100, v100
	v_exp_f32_e32 v101, v101
	v_exp_f32_e32 v102, v102
	v_exp_f32_e32 v103, v103
	v_exp_f32_e32 v104, v104
	v_exp_f32_e32 v105, v105
	v_cvt_pk_bf16_f32 v214, v98, v99
	v_cvt_pk_bf16_f32 v215, v100, v101
	v_cvt_pk_bf16_f32 v216, v102, v103
	v_cvt_pk_bf16_f32 v217, v104, v105
	ds_read_b64_tr_b16 v[226:227], v213 offset:14336
	ds_read_b64_tr_b16 v[230:231], v213 offset:14400
	ds_read_b64_tr_b16 v[234:235], v213 offset:14464
	ds_read_b64_tr_b16 v[238:239], v213 offset:14528
	ds_read_b64_tr_b16 v[228:229], v213 offset:16896
	ds_read_b64_tr_b16 v[232:233], v213 offset:16960
	ds_read_b64_tr_b16 v[236:237], v213 offset:17024
	ds_read_b64_tr_b16 v[240:241], v213 offset:17088
	s_setprio 1
	s_waitcnt lgkmcnt(11)
	v_mfma_f32_32x32x16_bf16 v[50:65], v[154:157], v[214:217], v[50:65]
	v_exp_f32_e32 v106, v106
	v_exp_f32_e32 v107, v107
	s_waitcnt lgkmcnt(10)
	v_mfma_f32_32x32x16_bf16 v[34:49], v[150:153], v[214:217], v[34:49]
	v_exp_f32_e32 v108, v108
	v_exp_f32_e32 v109, v109
	v_cvt_pk_bf16_f32 v218, v106, v107
	s_waitcnt lgkmcnt(9)
	v_mfma_f32_32x32x16_bf16 v[18:33], v[146:149], v[214:217], v[18:33]
	v_exp_f32_e32 v110, v110
	v_exp_f32_e32 v111, v111
	v_cvt_pk_bf16_f32 v219, v108, v109
	s_waitcnt lgkmcnt(8)
	v_mfma_f32_32x32x16_bf16 v[2:17], v[142:145], v[214:217], v[2:17]
	v_exp_f32_e32 v112, v112
	v_exp_f32_e32 v113, v113
	v_cvt_pk_bf16_f32 v220, v110, v111
	v_cvt_pk_bf16_f32 v221, v112, v113
	s_setprio 0
	ds_read_b64_tr_b16 v[142:143], v213 offset:19456
	ds_read_b64_tr_b16 v[146:147], v213 offset:19520
	ds_read_b64_tr_b16 v[150:151], v213 offset:19584
	ds_read_b64_tr_b16 v[154:155], v213 offset:19648
	ds_read_b64_tr_b16 v[144:145], v213 offset:22016
	ds_read_b64_tr_b16 v[148:149], v213 offset:22080
	ds_read_b64_tr_b16 v[152:153], v213 offset:22144
	ds_read_b64_tr_b16 v[156:157], v213 offset:22208
	s_setprio 1
	s_waitcnt lgkmcnt(11)
	v_mfma_f32_32x32x16_bf16 v[50:65], v[226:229], v[218:221], v[50:65]
	v_exp_f32_e32 v82, v82
	v_exp_f32_e32 v83, v83
	v_add_f32_e32 v98, v100, v98
	v_add_f32_e32 v99, v99, v101
	s_waitcnt lgkmcnt(10)
	v_mfma_f32_32x32x16_bf16 v[34:49], v[230:233], v[218:221], v[34:49]
	v_exp_f32_e32 v84, v84
	v_exp_f32_e32 v85, v85
	v_cvt_pk_bf16_f32 v222, v82, v83
	v_add_f32_e32 v98, v98, v102
	s_waitcnt lgkmcnt(9)
	v_mfma_f32_32x32x16_bf16 v[18:33], v[234:237], v[218:221], v[18:33]
	v_exp_f32_e32 v86, v86
	v_exp_f32_e32 v87, v87
	v_cvt_pk_bf16_f32 v223, v84, v85
	v_add_f32_e32 v99, v103, v99
	s_waitcnt lgkmcnt(8)
	v_mfma_f32_32x32x16_bf16 v[2:17], v[238:241], v[218:221], v[2:17]
	v_exp_f32_e32 v88, v88
	v_exp_f32_e32 v89, v89
	v_cvt_pk_bf16_f32 v224, v86, v87
	v_cvt_pk_bf16_f32 v225, v88, v89
	s_setprio 0
	ds_read_b64_tr_b16 v[214:215], v213 offset:24576
	ds_read_b64_tr_b16 v[218:219], v213 offset:24640
	ds_read_b64_tr_b16 v[226:227], v213 offset:24704
	ds_read_b64_tr_b16 v[230:231], v213 offset:24768
	ds_read_b64_tr_b16 v[216:217], v213 offset:27136
	ds_read_b64_tr_b16 v[220:221], v213 offset:27200
	ds_read_b64_tr_b16 v[228:229], v213 offset:27264
	ds_read_b64_tr_b16 v[232:233], v213 offset:27328
	s_setprio 1
	s_waitcnt lgkmcnt(11)
	v_mfma_f32_32x32x16_bf16 v[50:65], v[142:145], v[222:225], v[50:65]
	v_exp_f32_e32 v90, v90
	v_exp_f32_e32 v91, v91
	v_add_f32_e32 v98, v104, v98
	v_add_f32_e32 v99, v105, v99
	s_waitcnt lgkmcnt(10)
	v_mfma_f32_32x32x16_bf16 v[34:49], v[146:149], v[222:225], v[34:49]
	v_exp_f32_e32 v92, v92
	v_exp_f32_e32 v93, v93
	v_cvt_pk_bf16_f32 v242, v90, v91
	v_add_f32_e32 v98, v106, v98
	s_waitcnt lgkmcnt(9)
	v_mfma_f32_32x32x16_bf16 v[18:33], v[150:153], v[222:225], v[18:33]
	v_exp_f32_e32 v94, v94
	v_exp_f32_e32 v95, v95
	v_cvt_pk_bf16_f32 v243, v92, v93
	v_add_f32_e32 v99, v107, v99
	s_waitcnt lgkmcnt(8)
	v_mfma_f32_32x32x16_bf16 v[2:17], v[154:157], v[222:225], v[2:17]
	v_exp_f32_e32 v96, v96
	v_exp_f32_e32 v97, v97
	v_cvt_pk_bf16_f32 v244, v94, v95
	v_cvt_pk_bf16_f32 v245, v96, v97
	s_nop 1
	s_waitcnt lgkmcnt(3)
	v_mfma_f32_32x32x16_bf16 v[50:65], v[214:217], v[242:245], v[50:65]
	v_add_f32_e32 v98, v108, v98
	v_add_f32_e32 v99, v109, v99
	v_add_f32_e32 v98, v110, v98
	v_add_f32_e32 v99, v111, v99
	v_add_f32_e32 v98, v112, v98
	v_add_f32_e32 v99, v113, v99
	s_waitcnt lgkmcnt(2)
	v_mfma_f32_32x32x16_bf16 v[34:49], v[218:221], v[242:245], v[34:49]
	v_add_f32_e32 v82, v82, v98
	v_add_f32_e32 v83, v83, v99
	v_add_f32_e32 v82, v84, v82
	v_add_f32_e32 v83, v85, v83
	v_add_f32_e32 v82, v86, v82
	v_add_f32_e32 v83, v87, v83
	s_waitcnt lgkmcnt(1)
	v_mfma_f32_32x32x16_bf16 v[18:33], v[226:229], v[242:245], v[18:33]
	v_add_f32_e32 v82, v88, v82
	v_add_f32_e32 v83, v89, v83
	v_add_f32_e32 v82, v90, v82
	v_add_f32_e32 v83, v91, v83
	v_add_f32_e32 v82, v92, v82
	v_add_f32_e32 v83, v93, v83
	s_waitcnt lgkmcnt(0)
	v_mfma_f32_32x32x16_bf16 v[2:17], v[230:233], v[242:245], v[2:17]
	s_setprio 0
	v_add_f32_e32 v82, v94, v82
	v_add_f32_e32 v83, v95, v83
	v_add_f32_e32 v82, v96, v82
	v_add_f32_e32 v83, v97, v83
	v_add_f32_e32 v82, v82, v83
	v_add_f32_e32 v0, v0, v82
	s_cmp_lt_u32 s29, 62
	s_cbranch_scc1 .LBB0_801
	s_cmp_eq_u32 s10, 0x17a0000
	s_cbranch_scc1 .LBB0_801
	s_xor_b32 s12, s30, 1
	s_mulk_i32 s12, 0x7400
	s_add_i32 s12, s12, 0
	v_add3_u32 v142, s12, v206, v183
	s_waitcnt vmcnt(2)
	ds_write_b128 v142, v[130:133]
	v_add3_u32 v142, s12, v205, v207
	s_cmp_gt_u32 s29, 61
	s_waitcnt vmcnt(1)
	ds_write_b128 v142, v[134:137] offset:9216
	s_waitcnt vmcnt(0)
	ds_write_b128 v142, v[138:141] offset:19456
	s_cbranch_scc1 .LBB0_801
	v_lshl_add_u64 v[130:131], v[188:189], 0, s[10:11]
	v_lshl_add_u64 v[134:135], v[190:191], 0, s[10:11]
	v_lshl_add_u64 v[138:139], v[192:193], 0, s[10:11]
	global_load_dwordx4 v[130:133], v[130:131], off
	s_nop 0
	global_load_dwordx4 v[134:137], v[134:135], off
	s_nop 0
	global_load_dwordx4 v[138:141], v[138:139], off
	s_branch .LBB0_801
